# scan_rwkv loader waves convert FFN weight tiles of the conversion queue (own and partner scanner wave batches) with loads issued two segments ahead; conv_ensure finds them done
# speedup vs baseline: 1.0088x; 1.0022x over previous
.LBB0_1621:
	s_waitcnt lgkmcnt(0)
	s_add_u32 s14, s8, 0x3fa00000
	s_addc_u32 s15, s9, 0
	s_waitcnt lgkmcnt(0)
	s_barrier
	s_cmp_gt_i32 s40, 0
	v_and_b32_e32 v38, 15, v173
	s_cselect_b64 s[20:21], -1, 0
	s_cmp_lt_i32 s40, 1
	v_lshlrev_b32_e32 v40, 2, v43
	s_cbranch_scc1 .LBB0_1658
	s_lshl_b64 s[22:23], s[90:91], 11
	s_lshl_b64 s[24:25], s[90:91], 6
	s_add_i32 s3, 0, 0x1c000
	s_add_i32 s52, 0, 0x18000
	s_add_i32 s41, s40, -1
	s_add_u32 s42, s8, 0x33400000
	s_addc_u32 s43, s9, 0
	v_lshrrev_b32_e32 v0, 4, v2
	s_add_u32 s44, s8, 0x586c0000
	v_lshl_or_b32 v58, s2, 2, v0
	s_addc_u32 s45, s9, 0
	v_lshlrev_b32_e32 v0, 4, v58
	v_and_b32_e32 v2, 12, v38
	s_add_u32 s46, s8, 0x4c6c0000
	v_add3_u32 v59, s3, v0, v2
	v_lshlrev_b32_e32 v0, 8, v58
	v_lshlrev_b32_e32 v2, 4, v38
	s_addc_u32 s48, s9, 0
	s_lshl_b32 s2, s2, 10
	v_add3_u32 v60, s52, v0, v2
	s_add_i32 s49, s2, 0
	s_add_i32 s52, s52, s2
	v_readlane_b32 s2, v253, 53
	v_mov_b32_e32 v41, v1
	v_lshl_add_u32 v61, v43, 4, s3
	s_mul_i32 s2, s2, s38
	v_readlane_b32 s3, v253, 52
	v_lshlrev_b32_e32 v0, 6, v58
	v_lshl_add_u64 v[44:45], s[14:15], 0, v[40:41]
	v_lshrrev_b32_e32 v41, 4, v43
	s_sub_i32 s54, s3, s2
	s_not_b32 s2, s38
	v_readlane_b32 s3, v253, 2
	v_lshlrev_b32_e32 v42, 2, v38
	v_lshlrev_b32_e32 v46, 12, v41
	v_mov_b32_e32 v47, v1
	s_mul_i32 s55, s3, s2
	v_mov_b32_e32 v2, v1
	v_mov_b32_e32 v3, v1
	v_mov_b32_e32 v4, v1
	v_mov_b32_e32 v5, v1
	s_mov_b32 s57, 0
	s_movk_i32 s58, 0xf000
	s_movk_i32 s59, 0xc000
	v_lshlrev_b32_e32 v48, 2, v0
	v_lshlrev_b32_e32 v0, 2, v40
	v_lshlrev_b32_e32 v50, 2, v38
	v_readlane_b32 s60, v253, 3
	s_load_dwordx2 s[64:65], s[0:1], 0x1a8
	s_load_dwordx2 s[70:71], s[0:1], 0x10
	s_waitcnt lgkmcnt(0)
	s_add_i32 s98, s47, 0x20180
	v_mov_b32_e32 v111, s98
	ds_read_b64 v[112:113], v111
	v_and_b32_e32 v114, 7, v173
	v_bfe_u32 v115, v173, 3, 3
	v_mul_u32_u24_e32 v106, 0x2c000, v115
	v_lshl_add_u32 v106, v114, 4, v106
	v_lshlrev_b32_e32 v107, 16, v115
	v_lshl_add_u32 v107, v114, 4, v107
	v_lshlrev_b32_e32 v108, 14, v114
	v_lshl_add_u32 v108, v115, 4, v108
	v_mul_u32_u24_e32 v109, 0xb000, v114
	v_lshl_add_u32 v109, v115, 4, v109
	v_lshlrev_b32_e32 v110, 5, v115
	s_add_i32 s99, s98, -32
	v_mov_b32_e32 v120, s99
	ds_read_b64 v[118:119], v120
	s_mov_b32 s94, 0
	s_mov_b32 s95, 0
	s_waitcnt lgkmcnt(0)
	v_readfirstlane_b32 s2, v112
	v_readfirstlane_b32 s3, v113
	v_writelane_b32 v117, s2, 0
	v_writelane_b32 v117, s3, 1
	v_readfirstlane_b32 s92, v118
	v_readfirstlane_b32 s93, v119
	s_mov_b32 s4, 1
	v_writelane_b32 v117, s4, 2
	s_branch .LBB0_1625
.LBB0_1623:
	s_bitcmp1_b32 s57, 0
	s_cbranch_scc1 .Lcv_odd
	s_cmp_eq_u32 s57, 0
	s_cbranch_scc1 .Lcv_w0
	s_waitcnt vmcnt(16)
	s_branch .Lcv_w1
.Lcv_w0:
	s_waitcnt vmcnt(15)
.Lcv_w1:
	s_cmp_lt_u32 s94, 2
	s_cbranch_scc1 .Lcv_b_notitem
	s_cmp_eq_u32 s94, 2
	s_cbranch_scc0 .Lcv_b_cvt
	v_pk_mul_f32 v[130:131], v[130:131], v[162:163] op_sel_hi:[1,0]
	v_pk_mul_f32 v[132:133], v[132:133], v[162:163] op_sel_hi:[1,0]
	v_pk_mul_f32 v[134:135], v[134:135], v[162:163] op_sel:[0,1] op_sel_hi:[1,1]
	v_pk_mul_f32 v[136:137], v[136:137], v[162:163] op_sel:[0,1] op_sel_hi:[1,1]
	v_pk_mul_f32 v[138:139], v[138:139], v[164:165] op_sel_hi:[1,0]
	v_pk_mul_f32 v[140:141], v[140:141], v[164:165] op_sel_hi:[1,0]
	v_pk_mul_f32 v[142:143], v[142:143], v[164:165] op_sel:[0,1] op_sel_hi:[1,1]
	v_pk_mul_f32 v[144:145], v[144:145], v[164:165] op_sel:[0,1] op_sel_hi:[1,1]
	v_pk_mul_f32 v[146:147], v[146:147], v[166:167] op_sel_hi:[1,0]
	v_pk_mul_f32 v[148:149], v[148:149], v[166:167] op_sel_hi:[1,0]
	v_pk_mul_f32 v[150:151], v[150:151], v[166:167] op_sel:[0,1] op_sel_hi:[1,1]
	v_pk_mul_f32 v[152:153], v[152:153], v[166:167] op_sel:[0,1] op_sel_hi:[1,1]
	v_pk_mul_f32 v[154:155], v[154:155], v[168:169] op_sel_hi:[1,0]
	v_pk_mul_f32 v[156:157], v[156:157], v[168:169] op_sel_hi:[1,0]
	v_pk_mul_f32 v[158:159], v[158:159], v[168:169] op_sel:[0,1] op_sel_hi:[1,1]
	v_pk_mul_f32 v[160:161], v[160:161], v[168:169] op_sel:[0,1] op_sel_hi:[1,1]
.Lcv_b_cvt:
	v_cvt_pk_bf16_f32 v174, v130, v134
	v_cvt_pk_bf16_f32 v175, v138, v142
	v_cvt_pk_bf16_f32 v176, v146, v150
	v_cvt_pk_bf16_f32 v177, v154, v158
	v_cvt_pk_bf16_f32 v178, v131, v135
	v_cvt_pk_bf16_f32 v179, v139, v143
	v_cvt_pk_bf16_f32 v180, v147, v151
	v_cvt_pk_bf16_f32 v181, v155, v159
	v_cvt_pk_bf16_f32 v182, v132, v136
	v_cvt_pk_bf16_f32 v183, v140, v144
	v_cvt_pk_bf16_f32 v184, v148, v152
	v_cvt_pk_bf16_f32 v185, v156, v160
	v_cvt_pk_bf16_f32 v186, v133, v137
	v_cvt_pk_bf16_f32 v187, v141, v145
	v_cvt_pk_bf16_f32 v188, v149, v153
	v_cvt_pk_bf16_f32 v189, v157, v161
	s_cmp_eq_u32 s94, 2
	s_cbranch_scc0 .Lcv_b_st1
	global_store_dwordx4 v108, v[174:177], s[96:97]
	s_add_u32 s96, s96, 0x1000
	s_addc_u32 s97, s97, 0
	s_nop 0
	global_store_dwordx4 v108, v[178:181], s[96:97]
	s_add_u32 s96, s96, 0x1000
	s_addc_u32 s97, s97, 0
	s_nop 0
	global_store_dwordx4 v108, v[182:185], s[96:97]
	s_add_u32 s96, s96, 0x1000
	s_addc_u32 s97, s97, 0
	s_nop 0
	global_store_dwordx4 v108, v[186:189], s[96:97]
	s_branch .Lcv_b_done
.Lcv_b_st1:
	global_store_dwordx4 v109, v[174:177], s[96:97]
	s_add_u32 s96, s96, 0x2c00
	s_addc_u32 s97, s97, 0
	s_nop 0
	global_store_dwordx4 v109, v[178:181], s[96:97]
	s_add_u32 s96, s96, 0x2c00
	s_addc_u32 s97, s97, 0
	s_nop 0
	global_store_dwordx4 v109, v[182:185], s[96:97]
	s_add_u32 s96, s96, 0x2c00
	s_addc_u32 s97, s97, 0
	s_nop 0
	global_store_dwordx4 v109, v[186:189], s[96:97]
	s_branch .Lcv_b_done
.Lcv_b_notitem:
	global_store_dword v[44:45], v1, off
	global_store_dword v[44:45], v1, off
	global_store_dword v[44:45], v1, off
	global_store_dword v[44:45], v1, off
	s_cmp_eq_u32 s94, 1
	s_cbranch_scc0 .Lcv_b_done
	v_readfirstlane_b32 s2, v113
	s_add_i32 s92, s2, 0x5720
	s_sub_i32 s93, 0x27e40, s92
	s_min_i32 s93, s93, 16
	s_cmp_gt_i32 s93, 0
	s_cselect_b32 s93, s93, -1
.Lcv_b_done:
	s_mov_b32 s94, 0
	s_cmp_eq_u32 s95, 2
	s_cbranch_scc1 .Lcv_drain_ret
	s_cmp_lg_u32 s95, 0
	s_cbranch_scc1 .Lcv_pad10
.Lcv_a_top:
	s_cmp_gt_i32 s93, 0
	s_cbranch_scc1 .Lcv_a_item
	v_readlane_b32 s2, v117, 2
	s_cmp_eq_u32 s2, 1
	s_cbranch_scc1 .Lcv_switch
	s_cmp_lt_i32 s93, 0
	s_cbranch_scc1 .Lcv_a_stop
	s_load_dwordx2 s[2:3], s[0:1], 0x1b0
	v_mov_b32_e32 v113, 16
	s_waitcnt lgkmcnt(0)
	s_add_u32 s2, s2, 0x1000
	s_addc_u32 s3, s3, 0
	s_mov_b64 exec, 1
	global_atomic_add v113, v1, v113, s[2:3] sc0
	s_mov_b64 exec, -1
	s_mov_b32 s94, 1
	s_branch .Lcv_pad9
.Lcv_a_blocked:
	v_readlane_b32 s2, v117, 2
	s_cmp_eq_u32 s2, 1
	s_cbranch_scc1 .Lcv_switch
.Lcv_a_stop:
	s_mov_b32 s95, 1
	s_branch .Lcv_pad10
.Lcv_switch:
	s_add_i32 s2, s47, 0x20160
	v_mov_b32_e32 v111, s2
	v_mov_b32_e32 v112, s92
	v_mov_b32_e32 v113, s93
	s_mov_b64 exec, 1
	ds_write_b64 v111, v[112:113]
	s_mov_b64 exec, -1
	v_readlane_b32 s92, v117, 0
	v_readlane_b32 s93, v117, 1
	s_mov_b32 s2, 0
	v_writelane_b32 v117, s2, 2
	s_branch .Lcv_a_top
.Lcv_a_item:
	s_sub_i32 s3, s92, 0x5720
	s_mov_b32 s4, 0
	s_cmp_lt_u32 s92, 0xec20
	s_cbranch_scc1 .Lcv_q
	s_sub_i32 s3, s92, 0xec20
	s_mov_b32 s4, 1
	s_cmp_lt_u32 s92, 0x19640
	s_cbranch_scc1 .Lcv_q
	s_sub_i32 s3, s92, 0x19640
	s_mov_b32 s4, 2
	s_cmp_lt_u32 s92, 0x22b40
	s_cbranch_scc1 .Lcv_q
	s_sub_i32 s3, s92, 0x22b40
	s_mov_b32 s4, 3
.Lcv_q:
	s_sub_i32 s3, s3, 0x800
	s_cmp_lt_i32 s3, 0
	s_cbranch_scc1 .Lcv_a_blocked
	s_lshl_b32 s5, s4, 1
	s_add_i32 s5, s5, 1
	s_cmp_lt_u32 s3, 0x4200
	s_cbranch_scc1 .Lcv_seg
	s_sub_i32 s3, s3, 0x4b00
	s_cmp_lt_i32 s3, 0
	s_cbranch_scc1 .Lcv_a_blocked
	s_add_i32 s5, s5, 1
	s_cmp_lt_u32 s3, 0x4200
	s_cbranch_scc0 .Lcv_a_blocked
.Lcv_seg:
	s_cmp_lt_u32 s3, 0x2c00
	s_cbranch_scc0 .Lcv_k1
	s_cmp_ge_u32 s3, 0x1600
	s_cselect_b32 s18, 1, 0
	s_cselect_b32 s2, 0x1600, 0
	s_sub_i32 s3, s3, s2
	s_mul_i32 s91, s3, 0x1746
	s_lshr_b32 s91, s91, 20
	s_mul_i32 s4, s91, 0xb0
	s_sub_i32 s4, s3, s4
	s_lshr_b32 s2, s5, 1
	s_mul_i32 s61, s2, 0x2c00000
	s_lshl_b32 s62, s2, 13
	s_and_b32 s56, s5, 1
	s_mul_i32 s56, s56, 40
	s_mul_i32 s2, s91, 0x160000
	s_add_u32 s61, s61, s2
	s_lshl_b32 s2, s4, 7
	s_add_u32 s61, s61, s2
	s_lshl_b32 s2, s91, 8
	s_add_i32 s62, s62, s2
	s_lshr_b32 s66, s4, 2
	s_lshl_b32 s66, s66, 8
	s_and_b32 s2, s4, 3
	s_lshl_b32 s2, s2, 5
	s_add_i32 s66, s66, s2
	s_lshl_b32 s2, s18, 7
	s_add_i32 s66, s66, s2
	s_lshl_b32 s66, s66, 12
	s_mul_i32 s2, s5, 0x2c00000
	s_add_u32 s66, s66, s2
	s_add_u32 s66, s66, 0x200000
	s_lshl_b32 s2, s91, 7
	s_add_u32 s66, s66, s2
	s_lshl_b32 s4, s18, 3
	s_add_i32 s4, s4, s56
	s_add_i32 s4, s4, 0x58
	s_add_i32 s56, s56, 0x50
	s_load_dwordx2 s[32:33], s[0:1], s4
	s_load_dwordx2 s[2:3], s[0:1], s56
	s_load_dwordx2 s[98:99], s[0:1], 0x1b0
	s_waitcnt lgkmcnt(0)
	s_add_u32 s32, s32, s61
	s_addc_u32 s33, s33, 0
	s_add_u32 s2, s2, s62
	s_addc_u32 s3, s3, 0
	s_add_u32 s96, s98, s66
	s_addc_u32 s97, s99, 0
	s_nop 0
	global_load_dwordx4 v[162:165], v110, s[2:3]
	global_load_dwordx4 v[166:169], v110, s[2:3] offset:16
	global_load_dwordx4 v[130:133], v106, s[32:33] nt
	s_add_u32 s32, s32, 0x5800
	s_addc_u32 s33, s33, 0
	s_nop 0
	global_load_dwordx4 v[134:137], v106, s[32:33] nt
	s_add_u32 s32, s32, 0x5800
	s_addc_u32 s33, s33, 0
	s_nop 0
	global_load_dwordx4 v[138:141], v106, s[32:33] nt
	s_add_u32 s32, s32, 0x5800
	s_addc_u32 s33, s33, 0
	s_nop 0
	global_load_dwordx4 v[142:145], v106, s[32:33] nt
	s_add_u32 s32, s32, 0x5800
	s_addc_u32 s33, s33, 0
	s_nop 0
	global_load_dwordx4 v[146:149], v106, s[32:33] nt
	s_add_u32 s32, s32, 0x5800
	s_addc_u32 s33, s33, 0
	s_nop 0
	global_load_dwordx4 v[150:153], v106, s[32:33] nt
	s_add_u32 s32, s32, 0x5800
	s_addc_u32 s33, s33, 0
	s_nop 0
	global_load_dwordx4 v[154:157], v106, s[32:33] nt
	s_add_u32 s32, s32, 0x5800
	s_addc_u32 s33, s33, 0
	s_nop 0
	global_load_dwordx4 v[158:161], v106, s[32:33] nt
	s_mov_b32 s94, 2
	s_add_i32 s92, s92, 1
	s_sub_i32 s93, s93, 1
	s_branch .Lcv_pad0
.Lcv_k1:
	s_sub_i32 s3, s3, 0x2c00
	s_lshr_b32 s91, s3, 6
	s_and_b32 s4, s3, 63
	s_lshr_b32 s2, s5, 1
	s_mul_i32 s61, s2, 0x2c00000
	s_lshl_b32 s2, s91, 19
	s_add_u32 s61, s61, s2
	s_lshl_b32 s2, s4, 7
	s_add_u32 s61, s61, s2
	s_mul_i32 s66, s5, 0x1600000
	s_add_u32 s66, s66, 0x16200000
	s_mul_i32 s2, s4, 0x58000
	s_add_u32 s66, s66, s2
	s_lshl_b32 s2, s91, 7
	s_add_u32 s66, s66, s2
	s_and_b32 s4, s5, 1
	s_mul_i32 s4, s4, 40
	s_add_i32 s4, s4, 0x68
	s_load_dwordx2 s[32:33], s[0:1], s4
	s_load_dwordx2 s[98:99], s[0:1], 0x1b0
	s_waitcnt lgkmcnt(0)
	s_add_u32 s32, s32, s61
	s_addc_u32 s33, s33, 0
	s_add_u32 s96, s98, s66
	s_addc_u32 s97, s99, 0
	s_nop 0
	global_load_dwordx4 v[130:133], v107, s[32:33] nt
	s_add_u32 s32, s32, 0x2000
	s_addc_u32 s33, s33, 0
	s_nop 0
	global_load_dwordx4 v[134:137], v107, s[32:33] nt
	s_add_u32 s32, s32, 0x2000
	s_addc_u32 s33, s33, 0
	s_nop 0
	global_load_dwordx4 v[138:141], v107, s[32:33] nt
	s_add_u32 s32, s32, 0x2000
	s_addc_u32 s33, s33, 0
	s_nop 0
	global_load_dwordx4 v[142:145], v107, s[32:33] nt
	s_add_u32 s32, s32, 0x2000
	s_addc_u32 s33, s33, 0
	s_nop 0
	global_load_dwordx4 v[146:149], v107, s[32:33] nt
	s_add_u32 s32, s32, 0x2000
	s_addc_u32 s33, s33, 0
	s_nop 0
	global_load_dwordx4 v[150:153], v107, s[32:33] nt
	s_add_u32 s32, s32, 0x2000
	s_addc_u32 s33, s33, 0
	s_nop 0
	global_load_dwordx4 v[154:157], v107, s[32:33] nt
	s_add_u32 s32, s32, 0x2000
	s_addc_u32 s33, s33, 0
	s_nop 0
	global_load_dwordx4 v[158:161], v107, s[32:33] nt
	s_mov_b32 s94, 3
	s_add_i32 s92, s92, 1
	s_sub_i32 s93, s93, 1
	s_branch .Lcv_pad2
.Lcv_pad10:
	global_load_dword v116, v1, s[0:1]

.Lcv_odd:
	s_waitcnt vmcnt(30)

.LBB0_1648:
	s_cmp_lg_u32 s57, 1
	s_cbranch_scc0 .LBB0_1650
	s_nop 0
	s_mov_b64 s[26:27], 0
.LBB0_1650:
	s_andn2_b64 vcc, exec, s[26:27]
	s_cbranch_vccnz .LBB0_1652
	s_nop 0

.LBB0_1657:
	s_nop 0
	s_branch .LBB0_1623
.LBB0_1658:
	s_and_b64 vcc, exec, s[10:11]
	s_cbranch_vccz .Lcv_exit
	s_cmp_eq_u32 s94, 0
	s_cbranch_scc1 .Lcv_wb
	s_mov_b32 s95, 2
	s_waitcnt vmcnt(0)
	s_branch .Lcv_w1
.Lcv_drain_ret:
.Lcv_wb:
	v_readlane_b32 s2, v117, 2
	s_lshl_b32 s2, s2, 5
	s_sub_i32 s2, 0x20180, s2
	s_add_i32 s2, s2, s47
	v_mov_b32_e32 v111, s2
	v_mov_b32_e32 v112, s92
	v_mov_b32_e32 v113, s93
	s_mov_b64 exec, 1
	ds_write_b64 v111, v[112:113]
	s_mov_b64 exec, -1
